# XCD barrier: leader no longer bumps the unused per-XCD relay word (one atomic round trip less before the leader resumes)
# baseline (speedup 1.0000x reference)
.LBB0_127:
	s_or_b64 exec, exec, s[6:7]
	s_mov_b64 s[6:7], exec
	v_mbcnt_lo_u32_b32 v0, s6, 0
	v_mbcnt_hi_u32_b32 v0, s7, v0
	v_cmp_eq_u32_e32 vcc, 0, v0
	s_waitcnt vmcnt(0)
	buffer_inv sc1
	s_and_saveexec_b64 s[8:9], vcc
	s_cbranch_execz .LBB0_129
	s_bcnt1_i32_b64 s1, s[6:7]
	v_mov_b32_e32 v0, 0x2000
	v_mov_b32_e32 v1, s1
.LBB0_129:
	s_or_b64 exec, exec, s[8:9]
	s_waitcnt vmcnt(0)

.LBB0_248:
	s_or_b64 exec, exec, s[6:7]
	s_mov_b64 s[6:7], exec
	v_mbcnt_lo_u32_b32 v0, s6, 0
	v_mbcnt_hi_u32_b32 v0, s7, v0
	v_cmp_eq_u32_e32 vcc, 0, v0
	s_waitcnt vmcnt(0)
	buffer_inv sc1
	s_and_saveexec_b64 s[8:9], vcc
	s_cbranch_execz .LBB0_250
	s_bcnt1_i32_b64 s1, s[6:7]
	v_mov_b32_e32 v0, 0x2000
	v_mov_b32_e32 v1, s1
.LBB0_250:
	s_or_b64 exec, exec, s[8:9]
	s_waitcnt vmcnt(0)

.LBB0_790:
	s_or_b64 exec, exec, s[4:5]
	s_mov_b64 s[4:5], exec
	v_mbcnt_lo_u32_b32 v0, s4, 0
	v_mbcnt_hi_u32_b32 v0, s5, v0
	v_cmp_eq_u32_e32 vcc, 0, v0
	s_waitcnt vmcnt(0)
	buffer_inv sc1
	s_and_saveexec_b64 s[6:7], vcc
	s_cbranch_execz .LBB0_792
	s_bcnt1_i32_b64 s4, s[4:5]
	v_mov_b32_e32 v0, 0x2000
	v_mov_b32_e32 v1, s4
.LBB0_792:
	s_or_b64 exec, exec, s[6:7]
	s_waitcnt vmcnt(0)

.LBB0_900:
	s_or_b64 exec, exec, s[4:5]
	s_mov_b64 s[4:5], exec
	v_mbcnt_lo_u32_b32 v0, s4, 0
	v_mbcnt_hi_u32_b32 v0, s5, v0
	v_cmp_eq_u32_e32 vcc, 0, v0
	s_waitcnt vmcnt(0)
	buffer_inv sc1
	s_and_saveexec_b64 s[6:7], vcc
	s_cbranch_execz .LBB0_902
	s_bcnt1_i32_b64 s4, s[4:5]
	v_mov_b32_e32 v0, 0x2000
	v_mov_b32_e32 v1, s4
.LBB0_902:
	s_or_b64 exec, exec, s[6:7]
	s_waitcnt vmcnt(0)

.LBB0_969:
	s_or_b64 exec, exec, s[4:5]
	s_mov_b64 s[4:5], exec
	v_mbcnt_lo_u32_b32 v0, s4, 0
	v_mbcnt_hi_u32_b32 v0, s5, v0
	v_cmp_eq_u32_e32 vcc, 0, v0
	s_waitcnt vmcnt(0)
	buffer_inv sc1
	s_and_saveexec_b64 s[6:7], vcc
	s_cbranch_execz .LBB0_971
	s_bcnt1_i32_b64 s4, s[4:5]
	v_mov_b32_e32 v0, 0x2000
	v_mov_b32_e32 v1, s4
.LBB0_971:
	s_or_b64 exec, exec, s[6:7]
	s_waitcnt vmcnt(0)

.LBB0_1051:
	s_or_b64 exec, exec, s[6:7]
	s_mov_b64 s[6:7], exec
	v_mbcnt_lo_u32_b32 v0, s6, 0
	v_mbcnt_hi_u32_b32 v0, s7, v0
	v_cmp_eq_u32_e32 vcc, 0, v0
	s_waitcnt vmcnt(0)
	buffer_inv sc1
	s_and_saveexec_b64 s[8:9], vcc
	s_cbranch_execz .LBB0_1053
	s_bcnt1_i32_b64 s6, s[6:7]
	v_mov_b32_e32 v0, 0x2000
	v_mov_b32_e32 v1, s6
.LBB0_1053:
	s_or_b64 exec, exec, s[8:9]
	s_waitcnt vmcnt(0)

.LBB0_1145:
	s_or_b64 exec, exec, s[4:5]
	s_mov_b64 s[4:5], exec
	v_mbcnt_lo_u32_b32 v0, s4, 0
	v_mbcnt_hi_u32_b32 v0, s5, v0
	v_cmp_eq_u32_e32 vcc, 0, v0
	s_waitcnt vmcnt(0)
	buffer_inv sc1
	s_and_saveexec_b64 s[6:7], vcc
	s_cbranch_execz .LBB0_1147
	s_bcnt1_i32_b64 s4, s[4:5]
	v_mov_b32_e32 v0, 0x2000
	v_mov_b32_e32 v1, s4
.LBB0_1147:
	s_or_b64 exec, exec, s[6:7]
	s_waitcnt vmcnt(0)

.LBB0_1200:
	s_or_b64 exec, exec, s[4:5]
	s_mov_b64 s[4:5], exec
	v_mbcnt_lo_u32_b32 v0, s4, 0
	v_mbcnt_hi_u32_b32 v0, s5, v0
	v_cmp_eq_u32_e32 vcc, 0, v0
	s_waitcnt vmcnt(0)
	buffer_inv sc1
	s_and_saveexec_b64 s[6:7], vcc
	s_cbranch_execz .LBB0_1202
	s_bcnt1_i32_b64 s4, s[4:5]
	v_mov_b32_e32 v0, 0x2000
	v_mov_b32_e32 v1, s4
.LBB0_1202:
	s_or_b64 exec, exec, s[6:7]
	s_waitcnt vmcnt(0)

.LBB0_1275:
	s_or_b64 exec, exec, s[4:5]
	s_mov_b64 s[4:5], exec
	v_mbcnt_lo_u32_b32 v0, s4, 0
	v_mbcnt_hi_u32_b32 v0, s5, v0
	v_cmp_eq_u32_e32 vcc, 0, v0
	s_waitcnt vmcnt(0)
	buffer_inv sc1
	s_and_saveexec_b64 s[6:7], vcc
	s_cbranch_execz .LBB0_1277
	s_bcnt1_i32_b64 s4, s[4:5]
	v_mov_b32_e32 v0, 0x2000
	v_mov_b32_e32 v1, s4
.LBB0_1277:
	s_or_b64 exec, exec, s[6:7]
	s_waitcnt vmcnt(0)
